# v075: v074 + MLA attention softmax: pair-swap v_pk_mov_b32 feeding the bf16 converts removed (operands swapped in the converts instead)
# speedup vs baseline: 1.0295x; 1.0030x over previous
; template <int DQK, int DKA, int DV> ...
;     ...
;             float mxa = MAX3F(p0[0], p0[1], p1[0]), mxb = MAX3F(p0[2], p0[3], p1[1]); mxa = MAX3F(mxa, p1[2], p1[3]);
; #pragma unroll
;             for (int i = 4; i < 16; i += 4) { mxa = MAX3F(mxa, p0[i], p0[i + 1]); mxb = MAX3F(mxb, p0[i + 2], p0[i + 3]); mxa = MAX3F(mxa, p1[i], p1[i + 1]); mxb = MAX3F(mxb, p1[i + 2], p1[i + 3]); }
;             float mx = fmaxf(mxa, mxb);
;             { auto rr = __builtin_amdgcn_permlane32_swap(__float_as_uint(mx), __float_as_uint(mx), false, false); mx = fmaxf(__uint_as_float(rr[0]), __uint_as_float(rr[1])); }
;             if (!NEGM) mx -= m;
;             if (t == 0) {
;                 m = mx;
;                 if (NEGM) {
; #pragma unroll
;                     for (int i = 0; i < 16; ++i) { p0[i] -= mx; p1[i] -= mx; }
; #pragma unroll
;                     for (int i = 0; i < 16; ++i) negm[i] = -m;
;                 }
;             } else if (__any(mx > RESC_THR)) {
;                 const float dl = fmaxf(mx, 0.f), alpha = __builtin_amdgcn_exp2f(-dl); m += dl;
;                 if (NEGM) {
; #pragma unroll
;                     for (int i = 0; i < 16; ++i) { p0[i] -= dl; p1[i] -= dl; }
; #pragma unroll
;                     for (int i = 0; i < 16; ++i) negm[i] = -m;
;                 }
;                 l *= alpha;
; #pragma unroll
;                 for (int v = 0; v < NV; ++v)
; #pragma unroll
;                     for (int i = 0; i < 16; ++i) o[v][i] *= alpha;
;             }
;             { float rs = 0.f;
; #pragma unroll
;               for (int i = 0; i < 16; ++i) { p0[i] = __builtin_amdgcn_exp2f(NEGM ? p0[i] : p0[i] - m); p1[i] = __builtin_amdgcn_exp2f(NEGM ? p1[i] : p1[i] - m); rs += p0[i] + p1[i]; }
;               l += rs;
; #pragma unroll
;               for (int s = 0; s < 2; ++s) { u32x4 w0, w1;
;                 w0.x = cvtpk_s(p0[8 * s], p0[8 * s + 1]); w0.y = cvtpk_s(p0[8 * s + 2], p0[8 * s + 3]); w0.z = cvtpk_s(p0[8 * s + 4], p0[8 * s + 5]); w0.w = cvtpk_s(p0[8 * s + 6], p0[8 * s + 7]);
;                 w1.x = cvtpk_s(p1[8 * s], p1[8 * s + 1]); w1.y = cvtpk_s(p1[8 * s + 2], p1[8 * s + 3]); w1.z = cvtpk_s(p1[8 * s + 4], p1[8 * s + 5]); w1.w = cvtpk_s(p1[8 * s + 6], p1[8 * s + 7]);
;                 pf[s] = __builtin_bit_cast(bf16x8, w0); pf[2 + s] = __builtin_bit_cast(bf16x8, w1); } }
;             __builtin_amdgcn_sched_barrier(0);
.LBB0_597:
	v_max_f32_e32 v32, v1, v1
	v_max_f32_e32 v33, v0, v0
	v_max_f32_e32 v32, v33, v32
	v_max3_f32 v33, v2, v3, v17
	v_max3_f32 v32, v32, v16, v18
	v_max3_f32 v32, v32, v19, v4
	v_max3_f32 v33, v33, v6, v7
	v_max3_f32 v32, v32, v5, v20
	v_max3_f32 v33, v33, v22, v23
	v_max3_f32 v32, v32, v21, v8
	v_max3_f32 v33, v33, v10, v11
	v_max3_f32 v32, v32, v9, v24
	v_max3_f32 v33, v33, v26, v27
	v_max3_f32 v32, v32, v25, v12
	v_max3_f32 v33, v33, v14, v15
	v_max3_f32 v32, v32, v13, v28
	v_max3_f32 v33, v33, v30, v31
	v_max3_f32 v32, v32, v29, v33
	v_mov_b32_e32 v33, v32
	s_nop 1
	v_permlane32_swap_b32_e32 v32, v33
	v_max_f32_e32 v33, v33, v33
	v_max_f32_e32 v32, v32, v32
	v_max_f32_e32 v199, v32, v33
	v_sub_f32_e32 v16, v16, v199
	v_sub_f32_e32 v18, v18, v199
	v_sub_f32_e32 v20, v20, v199
	v_sub_f32_e32 v21, v21, v199
	v_sub_f32_e32 v0, v0, v199
	v_sub_f32_e32 v1, v1, v199
	v_sub_f32_e32 v2, v2, v199
	v_sub_f32_e32 v3, v3, v199
	v_sub_f32_e32 v4, v4, v199
	v_sub_f32_e32 v5, v5, v199
	v_sub_f32_e32 v19, v19, v199
	v_sub_f32_e32 v164, v31, v199
	v_sub_f32_e32 v6, v6, v199
	v_sub_f32_e32 v31, v7, v199
	v_exp_f32_e32 v171, v0
	v_exp_f32_e32 v172, v16
	v_exp_f32_e32 v16, v1
	v_exp_f32_e32 v175, v2
	v_exp_f32_e32 v206, v18
	v_exp_f32_e32 v18, v3
	v_exp_f32_e32 v1, v4
	v_exp_f32_e32 v3, v20
	v_exp_f32_e32 v0, v5
	v_exp_f32_e32 v2, v21
	v_exp_f32_e32 v207, v19
	v_exp_f32_e32 v5, v6
	v_exp_f32_e32 v4, v31
	v_sub_f32_e32 v22, v22, v199
	v_sub_f32_e32 v23, v23, v199
	v_sub_f32_e32 v17, v17, v199
	v_sub_f32_e32 v165, v8, v199
	v_sub_f32_e32 v166, v9, v199
	v_exp_f32_e32 v7, v22
	v_exp_f32_e32 v6, v23
	v_sub_f32_e32 v26, v26, v199
	v_sub_f32_e32 v29, v29, v199
	v_sub_f32_e32 v167, v10, v199
	v_sub_f32_e32 v168, v11, v199
	v_sub_f32_e32 v169, v12, v199
	v_sub_f32_e32 v170, v13, v199
	v_exp_f32_e32 v173, v17
	v_sub_f32_e32 v17, v14, v199
	v_pk_add_f32 v[8:9], v[0:1], v[2:3]
	v_exp_f32_e32 v13, v165
	v_exp_f32_e32 v12, v166
	v_sub_f32_e32 v24, v24, v199
	v_sub_f32_e32 v25, v25, v199
	v_add_f32_e32 v209, v18, v207
	v_exp_f32_e32 v21, v167
	v_exp_f32_e32 v23, v26
	v_exp_f32_e32 v20, v168
	v_exp_f32_e32 v26, v29
	v_exp_f32_e32 v29, v17
	v_cvt_pk_bf16_f32 v17, v175, v18
	v_cvt_pk_bf16_f32 v18, v1, v0
	v_sub_f32_e32 v27, v27, v199
	v_sub_f32_e32 v28, v28, v199
	v_sub_f32_e32 v174, v15, v199
	v_exp_f32_e32 v15, v24
	v_exp_f32_e32 v14, v25
	v_exp_f32_e32 v25, v169
	v_exp_f32_e32 v24, v170
	v_cvt_pk_bf16_f32 v19, v5, v4
	v_exp_f32_e32 v22, v27
	v_exp_f32_e32 v27, v28
	v_exp_f32_e32 v28, v174
	v_cvt_pk_bf16_f32 v166, v3, v2
	v_sub_f32_e32 v30, v30, v199
	v_cvt_pk_bf16_f32 v167, v7, v6
	v_exp_f32_e32 v31, v30
	v_cvt_pk_bf16_f32 v168, v13, v12
	v_exp_f32_e32 v30, v164
	v_cvt_pk_bf16_f32 v169, v21, v20
	v_add_f32_e32 v185, v171, v172
	v_cvt_pk_bf16_f32 v170, v25, v24
	v_add_f32_e32 v189, v16, v173
	v_cvt_pk_bf16_f32 v16, v171, v16
	v_cvt_pk_bf16_f32 v171, v29, v28
	v_cvt_pk_bf16_f32 v164, v172, v173
	v_cvt_pk_bf16_f32 v172, v15, v14
	v_add_f32_e32 v208, v175, v206
	v_cvt_pk_bf16_f32 v173, v23, v22
	v_pk_add_f32 v[10:11], v[4:5], v[6:7]
	v_cvt_pk_bf16_f32 v174, v27, v26
	v_pk_add_f32 v[176:177], v[12:13], v[14:15]
	v_cvt_pk_bf16_f32 v175, v31, v30
	v_add_f32_e32 v0, 0, v185
	v_add_f32_e32 v0, v189, v0
	v_add_f32_e32 v0, v208, v0
	v_add_f32_e32 v0, v209, v0
	v_add_f32_e32 v0, v9, v0
	v_add_f32_e32 v0, v8, v0
	v_add_f32_e32 v0, v11, v0
	v_add_f32_e32 v0, v10, v0
	v_add_f32_e32 v0, v177, v0
	v_pk_add_f32 v[178:179], v[20:21], v[22:23]
	v_add_f32_e32 v0, v176, v0
	v_add_f32_e32 v0, v179, v0
	v_pk_add_f32 v[200:201], v[24:25], v[26:27]
	v_add_f32_e32 v0, v178, v0
	v_add_f32_e32 v0, v201, v0
	v_pk_add_f32 v[202:203], v[28:29], v[30:31]
	v_add_f32_e32 v0, v200, v0
	v_xor_b32_e32 v32, 0x80000000, v199
	v_add_f32_e32 v0, v203, v0
	v_mov_b32_e32 v33, v32
	v_mov_b32_e32 v34, v32
	v_mov_b32_e32 v35, v32
	v_mov_b32_e32 v36, v32
	v_mov_b32_e32 v37, v32
	v_mov_b32_e32 v38, v32
	v_mov_b32_e32 v39, v32
	v_mov_b32_e32 v40, v32
	v_mov_b32_e32 v41, v32
	v_mov_b32_e32 v42, v32
	v_mov_b32_e32 v43, v32
	v_mov_b32_e32 v44, v32
	v_mov_b32_e32 v45, v32
	v_mov_b32_e32 v46, v32
	v_mov_b32_e32 v47, v32
	v_cvt_pk_bf16_f32 v165, v206, v207
	v_add_f32_e32 v176, v202, v0
	s_setprio 3
	s_waitcnt lgkmcnt(14)
	v_mfma_f32_32x32x16_bf16 v[0:15], v[156:159], v[16:19], 0
	v_add_f32_e32 v185, 0, v176
	s_waitcnt lgkmcnt(12)
	v_mfma_f32_32x32x16_bf16 v[16:31], v[160:163], v[16:19], 0
	s_waitcnt lgkmcnt(10)
	v_mfma_f32_32x32x16_bf16 v[0:15], v[152:155], v[168:171], v[0:15]
	s_waitcnt lgkmcnt(8)
	v_mfma_f32_32x32x16_bf16 v[16:31], v[148:151], v[168:171], v[16:31]
	s_waitcnt lgkmcnt(6)
	v_mfma_f32_32x32x16_bf16 v[0:15], v[144:147], v[164:167], v[0:15]
	s_waitcnt lgkmcnt(4)
	v_mfma_f32_32x32x16_bf16 v[16:31], v[140:143], v[164:167], v[16:31]
	s_waitcnt lgkmcnt(2)
	v_mfma_f32_32x32x16_bf16 v[0:15], v[136:139], v[172:175], v[0:15]
	s_waitcnt lgkmcnt(0)
	v_mfma_f32_32x32x16_bf16 v[16:31], v[132:135], v[172:175], v[16:31]
	s_setprio 0
	ds_read_b128 v[132:135], v197 offset:20128
	ds_read_b128 v[140:143], v197 offset:20096
	ds_read_b128 v[136:139], v197 offset:13472
	ds_read_b128 v[144:147], v197 offset:13440
	ds_read_b128 v[148:151], v197 offset:20064
	ds_read_b128 v[156:159], v197 offset:20032
	ds_read_b128 v[152:155], v197 offset:13408
	ds_read_b128 v[160:163], v197 offset:13376
	ds_read_b128 v[172:175], v197 offset:13312
	ds_read_b128 v[168:171], v197 offset:13344
	ds_read_b128 v[164:167], v197 offset:20000
	ds_read_b128 v[176:179], v197 offset:19968
	s_mov_b64 s[58:59], 0

; __device__ __forceinline__ unsigned cvtpk_s(float lo, float hi) { f32x2_t v = {lo, hi}; bf16x2_t b = __builtin_convertvector(v, bf16x2_t); return __builtin_bit_cast(unsigned, b); }
; #define ATT_KFRAG(slot) do { LAS const unsigned char* kb_ = lds + (slot) * C::KBYTES + koff; \
;     _Pragma("unroll") for (int d0 = 0; d0 < ND; ++d0) { kf[2 * d0] = *(LAS const bf16x8*)(kb_ + 32 * d0); kf[2 * d0 + 1] = *(LAS const bf16x8*)(kb_ + 32 * KP + 32 * d0); } } while (0)
; #define ATT_PV(vv) do { _Pragma("unroll") for (int s4 = 0; s4 < 4; ++s4) _Pragma("unroll") for (int j = 0; j < 2; ++j) { \
;         const bf16x8 vf = __builtin_shufflevector(vlo[j * 4 + s4], vhi[j * 4 + s4], 0, 1, 2, 3, 4, 5, 6, 7); o[(vv) + j] = MFMA32(vf, pf[s4], o[(vv) + j]); } } while (0)
; template <int DQK, int DKA, int DV> ...
;     ...
;             { float rs = 0.f;
; #pragma unroll
;               for (int i = 0; i < 16; ++i) { p0[i] = __builtin_amdgcn_exp2f(NEGM ? p0[i] : p0[i] - m); p1[i] = __builtin_amdgcn_exp2f(NEGM ? p1[i] : p1[i] - m); rs += p0[i] + p1[i]; }
;               l += rs;
; #pragma unroll
;               for (int s = 0; s < 2; ++s) { u32x4 w0, w1;
;                 w0.x = cvtpk_s(p0[8 * s], p0[8 * s + 1]); w0.y = cvtpk_s(p0[8 * s + 2], p0[8 * s + 3]); w0.z = cvtpk_s(p0[8 * s + 4], p0[8 * s + 5]); w0.w = cvtpk_s(p0[8 * s + 6], p0[8 * s + 7]);
;                 w1.x = cvtpk_s(p1[8 * s], p1[8 * s + 1]); w1.y = cvtpk_s(p1[8 * s + 2], p1[8 * s + 3]); w1.z = cvtpk_s(p1[8 * s + 4], p1[8 * s + 5]); w1.w = cvtpk_s(p1[8 * s + 6], p1[8 * s + 7]);
;                 pf[s] = __builtin_bit_cast(bf16x8, w0); pf[2 + s] = __builtin_bit_cast(bf16x8, w1); } }
;             __builtin_amdgcn_sched_barrier(0);
;             if (NV == 2) {
;                 __builtin_amdgcn_s_setprio(3); ATT_PV(0); __builtin_amdgcn_s_setprio(0);
;                 __builtin_amdgcn_sched_barrier(0);
;                 if (t + 1 < NT) ATT_KFRAG(ks1);
.LBB0_612:
	v_exp_f32_e32 v160, v64
	v_exp_f32_e32 v161, v48
	v_exp_f32_e32 v48, v65
	v_exp_f32_e32 v162, v49
	v_exp_f32_e32 v49, v66
	v_exp_f32_e32 v166, v67
	v_exp_f32_e32 v65, v52
	v_exp_f32_e32 v64, v53
	v_exp_f32_e32 v67, v54
	v_exp_f32_e32 v66, v55
	v_exp_f32_e32 v149, v72
	v_exp_f32_e32 v148, v73
	v_exp_f32_e32 v73, v74
	v_exp_f32_e32 v153, v58
	v_exp_f32_e32 v72, v75
	v_exp_f32_e32 v152, v59
	v_exp_f32_e32 v59, v76
	v_exp_f32_e32 v75, v60
	v_exp_f32_e32 v58, v77
	v_exp_f32_e32 v74, v61
	v_exp_f32_e32 v61, v78
	v_exp_f32_e32 v77, v62
	v_exp_f32_e32 v60, v79
	v_exp_f32_e32 v76, v63
	v_exp_f32_e32 v151, v56
	v_exp_f32_e32 v150, v57
	v_exp_f32_e32 v165, v50
	v_exp_f32_e32 v167, v51
	v_exp_f32_e32 v51, v68
	v_exp_f32_e32 v50, v69
	v_pk_add_f32 v[156:157], v[58:59], v[74:75]
	v_pk_add_f32 v[158:159], v[60:61], v[76:77]
	v_cvt_pk_bf16_f32 v54, v65, v64
	v_cvt_pk_bf16_f32 v55, v67, v66
	v_cvt_pk_bf16_f32 v56, v149, v148
	v_cvt_pk_bf16_f32 v57, v73, v72
	v_cvt_pk_bf16_f32 v58, v59, v58
	v_cvt_pk_bf16_f32 v59, v61, v60
	v_add_f32_e32 v163, v160, v161
	v_pk_add_f32 v[68:69], v[50:51], v[64:65]
	v_cvt_pk_bf16_f32 v60, v151, v150
	v_cvt_pk_bf16_f32 v61, v153, v152
	v_pk_mov_b32 v[64:65], v[76:77], v[76:77] op_sel:[1,0]
	v_add_f32_e32 v164, v48, v162
	v_cvt_pk_bf16_f32 v62, v75, v74
	v_cvt_pk_bf16_f32 v63, v64, v65
	v_add_f32_e32 v64, 0, v163
	v_exp_f32_e32 v53, v70
	v_exp_f32_e32 v52, v71
	v_add_f32_e32 v168, v49, v165
	v_add_f32_e32 v64, v164, v64
	v_add_f32_e32 v169, v166, v167
	v_add_f32_e32 v64, v168, v64
	v_add_f32_e32 v64, v169, v64
	v_add_f32_e32 v64, v69, v64
	v_pk_add_f32 v[70:71], v[52:53], v[66:67]
	v_add_f32_e32 v64, v68, v64
	v_add_f32_e32 v64, v71, v64
	v_pk_add_f32 v[78:79], v[148:149], v[150:151]
	v_add_f32_e32 v64, v70, v64
	v_add_f32_e32 v64, v79, v64
	v_pk_add_f32 v[154:155], v[72:73], v[152:153]
	v_add_f32_e32 v64, v78, v64
	v_add_f32_e32 v64, v155, v64
	v_add_f32_e32 v64, v154, v64
	v_add_f32_e32 v64, v157, v64
	v_add_f32_e32 v64, v156, v64
	v_add_f32_e32 v64, v159, v64
	v_cvt_pk_bf16_f32 v48, v160, v48
	v_cvt_pk_bf16_f32 v49, v49, v166
	v_cvt_pk_bf16_f32 v50, v51, v50
	v_cvt_pk_bf16_f32 v51, v53, v52
	v_cvt_pk_bf16_f32 v52, v161, v162
	v_cvt_pk_bf16_f32 v53, v165, v167
	v_add_f32_e32 v64, v158, v64
	s_setprio 3
	s_waitcnt lgkmcnt(14)
	v_mfma_f32_32x32x16_bf16 v[0:15], v[144:147], v[48:51], v[0:15]
	v_add_f32_e32 v185, v185, v64
	s_waitcnt lgkmcnt(12)
	v_mfma_f32_32x32x16_bf16 v[16:31], v[140:143], v[48:51], v[16:31]
	s_waitcnt lgkmcnt(10)
	v_mfma_f32_32x32x16_bf16 v[0:15], v[136:139], v[56:59], v[0:15]
	s_waitcnt lgkmcnt(8)
	v_mfma_f32_32x32x16_bf16 v[16:31], v[132:135], v[56:59], v[16:31]
	s_waitcnt lgkmcnt(6)
	v_mfma_f32_32x32x16_bf16 v[0:15], v[128:131], v[52:55], v[0:15]
	s_waitcnt lgkmcnt(4)
	v_mfma_f32_32x32x16_bf16 v[16:31], v[124:127], v[52:55], v[16:31]
	s_waitcnt lgkmcnt(2)
	v_mfma_f32_32x32x16_bf16 v[0:15], v[120:123], v[60:63], v[0:15]
	s_waitcnt lgkmcnt(0)
	v_mfma_f32_32x32x16_bf16 v[16:31], v[116:119], v[60:63], v[16:31]
	s_setprio 0
	s_mul_i32 s22, s62, 0x3400
	v_add_u32_e32 v48, s22, v197
	ds_read_b128 v[132:135], v48 offset:6816
	ds_read_b128 v[140:143], v48 offset:6784
	ds_read_b128 v[136:139], v48 offset:160
	ds_read_b128 v[144:147], v48 offset:128
	ds_read_b128 v[148:151], v48 offset:6752
	ds_read_b128 v[156:159], v48 offset:6720
	ds_read_b128 v[152:155], v48 offset:96
	ds_read_b128 v[160:163], v48 offset:64
	ds_read_b128 v[172:175], v48
	ds_read_b128 v[168:171], v48 offset:32
	ds_read_b128 v[164:167], v48 offset:6688
	ds_read_b128 v[176:179], v48 offset:6656

; __device__ __forceinline__ unsigned cvtpk_s(float lo, float hi) { f32x2_t v = {lo, hi}; bf16x2_t b = __builtin_convertvector(v, bf16x2_t); return __builtin_bit_cast(unsigned, b); }
; #define ATT_KFRAG(slot) do { LAS const unsigned char* kb_ = lds + (slot) * C::KBYTES + koff; \
;     _Pragma("unroll") for (int d0 = 0; d0 < ND; ++d0) { kf[2 * d0] = *(LAS const bf16x8*)(kb_ + 32 * d0); kf[2 * d0 + 1] = *(LAS const bf16x8*)(kb_ + 32 * KP + 32 * d0); } } while (0)
; #define ATT_PV(vv) do { _Pragma("unroll") for (int s4 = 0; s4 < 4; ++s4) _Pragma("unroll") for (int j = 0; j < 2; ++j) { \
;         const bf16x8 vf = __builtin_shufflevector(vlo[j * 4 + s4], vhi[j * 4 + s4], 0, 1, 2, 3, 4, 5, 6, 7); o[(vv) + j] = MFMA32(vf, pf[s4], o[(vv) + j]); } } while (0)
; template <int DQK, int DKA, int DV> ...
;     ...
;             { float rs = 0.f;
; #pragma unroll
;               for (int i = 0; i < 16; ++i) { p0[i] = __builtin_amdgcn_exp2f(NEGM ? p0[i] : p0[i] - m); p1[i] = __builtin_amdgcn_exp2f(NEGM ? p1[i] : p1[i] - m); rs += p0[i] + p1[i]; }
;               l += rs;
; #pragma unroll
;               for (int s = 0; s < 2; ++s) { u32x4 w0, w1;
;                 w0.x = cvtpk_s(p0[8 * s], p0[8 * s + 1]); w0.y = cvtpk_s(p0[8 * s + 2], p0[8 * s + 3]); w0.z = cvtpk_s(p0[8 * s + 4], p0[8 * s + 5]); w0.w = cvtpk_s(p0[8 * s + 6], p0[8 * s + 7]);
;                 w1.x = cvtpk_s(p1[8 * s], p1[8 * s + 1]); w1.y = cvtpk_s(p1[8 * s + 2], p1[8 * s + 3]); w1.z = cvtpk_s(p1[8 * s + 4], p1[8 * s + 5]); w1.w = cvtpk_s(p1[8 * s + 6], p1[8 * s + 7]);
;                 pf[s] = __builtin_bit_cast(bf16x8, w0); pf[2 + s] = __builtin_bit_cast(bf16x8, w1); } }
;             __builtin_amdgcn_sched_barrier(0);
;             if (NV == 2) {
;                 __builtin_amdgcn_s_setprio(3); ATT_PV(0); __builtin_amdgcn_s_setprio(0);
;                 __builtin_amdgcn_sched_barrier(0);
;                 if (t + 1 < NT) ATT_KFRAG(ks1);
.LBB0_634:
	s_waitcnt vmcnt(0)
	v_exp_f32_e32 v108, v48
	v_exp_f32_e32 v109, v32
	v_exp_f32_e32 v32, v49
	v_exp_f32_e32 v110, v33
	v_exp_f32_e32 v33, v50
	v_exp_f32_e32 v114, v51
	v_exp_f32_e32 v49, v36
	v_exp_f32_e32 v48, v37
	v_exp_f32_e32 v51, v38
	v_exp_f32_e32 v50, v39
	v_exp_f32_e32 v97, v56
	v_exp_f32_e32 v96, v57
	v_exp_f32_e32 v57, v58
	v_exp_f32_e32 v101, v42
	v_exp_f32_e32 v56, v59
	v_exp_f32_e32 v100, v43
	v_exp_f32_e32 v43, v60
	v_exp_f32_e32 v59, v44
	v_exp_f32_e32 v42, v61
	v_exp_f32_e32 v58, v45
	v_exp_f32_e32 v45, v62
	v_exp_f32_e32 v61, v46
	v_exp_f32_e32 v44, v63
	v_exp_f32_e32 v60, v47
	v_exp_f32_e32 v99, v40
	v_exp_f32_e32 v98, v41
	v_exp_f32_e32 v113, v34
	v_exp_f32_e32 v115, v35
	v_exp_f32_e32 v35, v52
	v_exp_f32_e32 v34, v53
	v_pk_add_f32 v[104:105], v[42:43], v[58:59]
	v_pk_add_f32 v[106:107], v[44:45], v[60:61]
	v_cvt_pk_bf16_f32 v38, v49, v48
	v_cvt_pk_bf16_f32 v39, v51, v50
	v_cvt_pk_bf16_f32 v40, v97, v96
	v_cvt_pk_bf16_f32 v41, v57, v56
	v_cvt_pk_bf16_f32 v42, v43, v42
	v_cvt_pk_bf16_f32 v43, v45, v44
	v_add_f32_e32 v111, v108, v109
	v_pk_add_f32 v[52:53], v[34:35], v[48:49]
	v_cvt_pk_bf16_f32 v44, v99, v98
	v_cvt_pk_bf16_f32 v45, v101, v100
	v_pk_mov_b32 v[48:49], v[60:61], v[60:61] op_sel:[1,0]
	v_add_f32_e32 v112, v32, v110
	v_cvt_pk_bf16_f32 v46, v59, v58
	v_cvt_pk_bf16_f32 v47, v48, v49
	v_add_f32_e32 v48, 0, v111
	v_exp_f32_e32 v37, v54
	v_exp_f32_e32 v36, v55
	v_add_f32_e32 v116, v33, v113
	v_add_f32_e32 v48, v112, v48
	v_add_f32_e32 v117, v114, v115
	v_add_f32_e32 v48, v116, v48
	v_add_f32_e32 v48, v117, v48
	v_add_f32_e32 v48, v53, v48
	v_pk_add_f32 v[54:55], v[36:37], v[50:51]
	v_add_f32_e32 v48, v52, v48
	v_add_f32_e32 v48, v55, v48
	v_pk_add_f32 v[62:63], v[96:97], v[98:99]
	v_add_f32_e32 v48, v54, v48
	v_add_f32_e32 v48, v63, v48
	v_pk_add_f32 v[102:103], v[56:57], v[100:101]
	v_add_f32_e32 v48, v62, v48
	v_add_f32_e32 v48, v103, v48
	v_add_f32_e32 v48, v102, v48
	v_add_f32_e32 v48, v105, v48
	v_add_f32_e32 v48, v104, v48
	v_add_f32_e32 v48, v107, v48
	v_cvt_pk_bf16_f32 v32, v108, v32
	v_cvt_pk_bf16_f32 v33, v33, v114
	v_cvt_pk_bf16_f32 v34, v35, v34
	v_cvt_pk_bf16_f32 v35, v37, v36
	v_cvt_pk_bf16_f32 v36, v109, v110
	v_cvt_pk_bf16_f32 v37, v113, v115
	v_add_f32_e32 v48, v106, v48
	s_setprio 3
	s_waitcnt lgkmcnt(14)
	v_mfma_f32_32x32x16_bf16 v[0:15], v[92:95], v[32:35], v[0:15]
	v_add_f32_e32 v185, v185, v48
	s_waitcnt lgkmcnt(12)
	v_mfma_f32_32x32x16_bf16 v[16:31], v[88:91], v[32:35], v[16:31]
	s_waitcnt lgkmcnt(10)
	v_mfma_f32_32x32x16_bf16 v[0:15], v[84:87], v[40:43], v[0:15]
	s_waitcnt lgkmcnt(8)
	v_mfma_f32_32x32x16_bf16 v[16:31], v[80:83], v[40:43], v[16:31]
	s_waitcnt lgkmcnt(6)
	v_mfma_f32_32x32x16_bf16 v[0:15], v[76:79], v[36:39], v[0:15]
	s_waitcnt lgkmcnt(4)
	v_mfma_f32_32x32x16_bf16 v[16:31], v[72:75], v[36:39], v[16:31]
	s_waitcnt lgkmcnt(2)
	v_mfma_f32_32x32x16_bf16 v[0:15], v[68:71], v[44:47], v[0:15]
	s_waitcnt lgkmcnt(0)
	v_mfma_f32_32x32x16_bf16 v[16:31], v[64:67], v[44:47], v[16:31]
	s_setprio 0
	s_bitcmp1_b32 s8, 0
	s_cselect_b64 s[0:1], -1, 0
	s_and_b64 vcc, exec, s[0:1]
	s_cbranch_vccnz .LBB0_573
